# attention: prefetched V fragment reads stay in flight across the step barrier (counted lgkmcnt instead of a full drain)
# speedup vs baseline: 1.0043x; 1.0043x over previous
.Lamla_loop:
	ds_read_b128 v[136:139], v243 offset:0
	ds_read_b128 v[140:143], v243 offset:6656
	ds_read_b128 v[144:147], v243 offset:32
	ds_read_b128 v[148:151], v243 offset:6688
	s_waitcnt lgkmcnt(10)
	v_mfma_f32_32x32x16_bf16 v[0:15], v[176:179], v[96:99], v[0:15]
	v_max3_f32 v168, v64, v65, v66
	v_max3_f32 v170, v80, v81, v82
	v_max3_f32 v168, v168, v67, v68
	v_max3_f32 v170, v170, v83, v84
	v_max3_f32 v168, v168, v69, v70
	v_max3_f32 v170, v170, v85, v86
	s_mov_b32 s55, s52
	s_mov_b32 s52, s53
	s_mov_b32 s53, s54
	s_mov_b32 s54, s55
	s_mov_b32 s9, 0
	s_waitcnt lgkmcnt(8)
	v_mfma_f32_32x32x16_bf16 v[16:31], v[180:183], v[96:99], v[16:31]
	v_max3_f32 v168, v168, v71, v72
	v_max3_f32 v170, v170, v87, v88
	v_max3_f32 v168, v168, v73, v74
	v_max3_f32 v170, v170, v89, v90
	v_max3_f32 v168, v168, v75, v76
	v_max3_f32 v170, v170, v91, v92
	global_load_dwordx4 v[152:155], v225, s[2:3]
	global_load_dwordx2 v[160:161], v165, s[10:11]
	global_load_dwordx4 v[156:159], v225, s[4:5]
	s_add_u32 s2, s2, 0x2000
	s_addc_u32 s3, s3, 0
	s_add_u32 s10, s10, 0x1000
	s_addc_u32 s11, s11, 0
	s_add_u32 s4, s4, 0x2000
	s_addc_u32 s5, s5, 0
	v_add_u32_e32 v222, s53, v220
	v_add_u32_e32 v224, s54, v221
	v_mfma_f32_32x32x16_bf16 v[226:241], v[246:249], v[96:99], v[226:241]
	v_max3_f32 v168, v168, v77, v78
	v_max3_f32 v170, v170, v93, v94
	v_max_f32_e32 v168, v168, v79
	v_max_f32_e32 v170, v170, v95
	v_max_f32_e32 v168, v168, v170
	s_waitcnt lgkmcnt(3)
	v_mfma_f32_32x32x16_bf16 v[32:47], v[136:139], v[112:115], 0
	v_mov_b32_e32 v170, v168
	s_nop 1
	v_permlane32_swap_b32_e32 v168, v170
	v_max_f32_e32 v168, v168, v170
	v_mul_f32_e32 v168, 0x3e16c740, v168
	v_cmp_gt_f32_e32 vcc, v168, v164
	s_cbranch_vccz .Lamla_nors_2
	v_max_f32_e32 v170, v162, v168
	v_sub_f32_e32 v166, v162, v170
	v_exp_f32_e32 v166, v166
	v_mov_b32_e32 v162, v170
	v_add_f32_e32 v164, 0x41000000, v170
	v_xor_b32_e32 v163, 0x80000000, v170
	s_mov_b32 s9, 1

.Lamla_noresc_3:
	s_barrier
	ds_read_b128 v[136:139], v243 offset:13312
	ds_read_b128 v[140:143], v243 offset:19968
	ds_read_b128 v[144:147], v243 offset:13344
	ds_read_b128 v[148:151], v243 offset:20000
	s_waitcnt lgkmcnt(10)
	v_mfma_f32_32x32x16_bf16 v[0:15], v[176:179], v[96:99], v[0:15]
	v_max3_f32 v168, v32, v33, v34
	v_max3_f32 v170, v48, v49, v50
	v_max3_f32 v168, v168, v35, v36
	v_max3_f32 v170, v170, v51, v52
	v_max3_f32 v168, v168, v37, v38
	v_max3_f32 v170, v170, v53, v54
	s_mov_b32 s55, s52
	s_mov_b32 s52, s53
	s_mov_b32 s53, s54
	s_mov_b32 s54, s55
	s_mov_b32 s9, 0
	s_waitcnt lgkmcnt(8)
	v_mfma_f32_32x32x16_bf16 v[16:31], v[180:183], v[96:99], v[16:31]
	v_max3_f32 v168, v168, v39, v40
	v_max3_f32 v170, v170, v55, v56
	v_max3_f32 v168, v168, v41, v42
	v_max3_f32 v170, v170, v57, v58
	v_max3_f32 v168, v168, v43, v44
	v_max3_f32 v170, v170, v59, v60
	global_load_dwordx4 v[208:211], v225, s[2:3]
	global_load_dwordx2 v[216:217], v165, s[10:11]
	global_load_dwordx4 v[212:215], v225, s[4:5]
	s_add_u32 s2, s2, 0x2000
	s_addc_u32 s3, s3, 0
	s_add_u32 s10, s10, 0x1000
	s_addc_u32 s11, s11, 0
	s_add_u32 s4, s4, 0x2000
	s_addc_u32 s5, s5, 0
	v_add_u32_e32 v223, s53, v220
	v_add_u32_e32 v224, s54, v221
	v_mfma_f32_32x32x16_bf16 v[226:241], v[246:249], v[96:99], v[226:241]
	v_max3_f32 v168, v168, v45, v46
	v_max3_f32 v170, v170, v61, v62
	v_max_f32_e32 v168, v168, v47
	v_max_f32_e32 v170, v170, v63
	v_max_f32_e32 v168, v168, v170
	s_waitcnt lgkmcnt(3)
	v_mfma_f32_32x32x16_bf16 v[64:79], v[136:139], v[112:115], 0
	v_mov_b32_e32 v170, v168
	s_nop 1
	v_permlane32_swap_b32_e32 v168, v170
	v_max_f32_e32 v168, v168, v170
	v_mul_f32_e32 v168, 0x3e16c740, v168
	v_cmp_gt_f32_e32 vcc, v168, v164
	s_cbranch_vccz .Lamla_nors_4
	v_max_f32_e32 v170, v162, v168
	v_sub_f32_e32 v166, v162, v170
	v_exp_f32_e32 v166, v166
	v_mov_b32_e32 v162, v170
	v_add_f32_e32 v164, 0x41000000, v170
	v_xor_b32_e32 v163, 0x80000000, v170
	s_mov_b32 s9, 1

; #define AT_STEP(SC0, SC1, SN0, SN1, t, DOK, DOV) do { \
;             if (DOK) AT_GLOADK(((t) + 2) * 64); \
;             if (DOV) { AT_GLOADV(((t) + 1) * 64); AT_QK(SN0, SN1, ((t) + 1) & 1); } \
;             AT_SMPV(SC0, SC1, (t) & 1); \
;             if (DOK) AT_WRITEK((t) & 1); \
;             if (DOV) AT_WRITEV(((t) + 1) & 1); \
;             __syncthreads(); } while (0)
; template <bool MLA>
; DI void attn_phase(const int TID, const int BID, LAS unsigned char* lds, const Params& p, bool need_ctx) {
;     ...
;         for (; t < ntile - 2; t += 2) {
;             AT_STEP(sa0, sa1, sb0, sb1, t, true, true);
;             AT_STEP(sb0, sb1, sa0, sa1, t + 1, true, true);
;         }
;         AT_STEP(sa0, sa1, sb0, sb1, t, false, true);
;         AT_STEP(sb0, sb1, sa0, sa1, t + 1, false, false);
.Lamla_noresc_5:
	s_barrier
	s_add_i32 s7, s7, -1
	s_cmp_lg_u32 s7, 0
	s_cbranch_scc1 .Lamla_loop
.Lamla_tail:
	ds_read_b128 v[136:139], v243 offset:0
	ds_read_b128 v[140:143], v243 offset:6656
	ds_read_b128 v[144:147], v243 offset:32
	ds_read_b128 v[148:151], v243 offset:6688
	s_waitcnt lgkmcnt(10)
	v_mfma_f32_32x32x16_bf16 v[0:15], v[176:179], v[96:99], v[0:15]
	v_max3_f32 v168, v64, v65, v66
	v_max3_f32 v170, v80, v81, v82
	v_max3_f32 v168, v168, v67, v68
	v_max3_f32 v170, v170, v83, v84
	v_max3_f32 v168, v168, v69, v70
	v_max3_f32 v170, v170, v85, v86
	s_mov_b32 s55, s52
	s_mov_b32 s52, s53
	s_mov_b32 s53, s54
	s_mov_b32 s54, s55
	s_mov_b32 s9, 0
	s_waitcnt lgkmcnt(8)
	v_mfma_f32_32x32x16_bf16 v[16:31], v[180:183], v[96:99], v[16:31]
	v_max3_f32 v168, v168, v71, v72
	v_max3_f32 v170, v170, v87, v88
	v_max3_f32 v168, v168, v73, v74
	v_max3_f32 v170, v170, v89, v90
	v_max3_f32 v168, v168, v75, v76
	v_max3_f32 v170, v170, v91, v92
	global_load_dwordx4 v[156:159], v225, s[4:5]
	s_add_u32 s4, s4, 0x2000
	s_addc_u32 s5, s5, 0
	v_add_u32_e32 v222, s53, v220
	v_add_u32_e32 v224, s54, v221
	v_mfma_f32_32x32x16_bf16 v[226:241], v[246:249], v[96:99], v[226:241]
	v_max3_f32 v168, v168, v77, v78
	v_max3_f32 v170, v170, v93, v94
	v_max_f32_e32 v168, v168, v79
	v_max_f32_e32 v170, v170, v95
	v_max_f32_e32 v168, v168, v170
	s_waitcnt lgkmcnt(3)
	v_mfma_f32_32x32x16_bf16 v[32:47], v[136:139], v[112:115], 0
	v_mov_b32_e32 v170, v168
	s_nop 1
	v_permlane32_swap_b32_e32 v168, v170
	v_max_f32_e32 v168, v168, v170
	v_mul_f32_e32 v168, 0x3e16c740, v168
	v_cmp_gt_f32_e32 vcc, v168, v164
	s_cbranch_vccz .Lamla_nors_6
	v_max_f32_e32 v170, v162, v168
	v_sub_f32_e32 v166, v162, v170
	v_exp_f32_e32 v166, v166
	v_mov_b32_e32 v162, v170
	v_add_f32_e32 v164, 0x41000000, v170
	v_xor_b32_e32 v163, 0x80000000, v170
	s_mov_b32 s9, 1

.Lamla_noresc_7:
	s_barrier
	ds_read_b128 v[136:139], v243 offset:13312
	ds_read_b128 v[140:143], v243 offset:19968
	ds_read_b128 v[144:147], v243 offset:13344
	ds_read_b128 v[148:151], v243 offset:20000
	s_waitcnt lgkmcnt(10)
	v_mfma_f32_32x32x16_bf16 v[0:15], v[176:179], v[96:99], v[0:15]
	v_max3_f32 v168, v32, v33, v34
	v_max3_f32 v170, v48, v49, v50
	v_max3_f32 v168, v168, v35, v36
	v_max3_f32 v170, v170, v51, v52
	v_max3_f32 v168, v168, v37, v38
	v_max3_f32 v170, v170, v53, v54
	s_mov_b32 s55, s52
	s_mov_b32 s52, s53
	s_mov_b32 s53, s54
	s_mov_b32 s54, s55
	s_mov_b32 s9, 0
	s_waitcnt lgkmcnt(8)
	v_mfma_f32_32x32x16_bf16 v[16:31], v[180:183], v[96:99], v[16:31]
	v_max3_f32 v168, v168, v39, v40
	v_max3_f32 v170, v170, v55, v56
	v_max3_f32 v168, v168, v41, v42
	v_max3_f32 v170, v170, v57, v58
	v_max3_f32 v168, v168, v43, v44
	v_max3_f32 v170, v170, v59, v60
	v_add_u32_e32 v223, s53, v220
	v_add_u32_e32 v224, s54, v221
	v_mfma_f32_32x32x16_bf16 v[226:241], v[246:249], v[96:99], v[226:241]
	v_max3_f32 v168, v168, v45, v46
	v_max3_f32 v170, v170, v61, v62
	v_max_f32_e32 v168, v168, v47
	v_max_f32_e32 v170, v170, v63
	v_max_f32_e32 v168, v168, v170
	s_waitcnt lgkmcnt(3)
	v_mfma_f32_32x32x16_bf16 v[64:79], v[136:139], v[112:115], 0
	v_mov_b32_e32 v170, v168
	s_nop 1
	v_permlane32_swap_b32_e32 v168, v170
	v_max_f32_e32 v168, v168, v170
	v_mul_f32_e32 v168, 0x3e16c740, v168
	v_cmp_gt_f32_e32 vcc, v168, v164
	s_cbranch_vccz .Lamla_nors_8
	v_max_f32_e32 v170, v162, v168
	v_sub_f32_e32 v166, v162, v170
	v_exp_f32_e32 v166, v166
	v_mov_b32_e32 v162, v170
	v_add_f32_e32 v164, 0x41000000, v170
	v_xor_b32_e32 v163, 0x80000000, v170
	s_mov_b32 s9, 1

; template <bool MLA>
; DI void attn_phase(const int TID, const int BID, LAS unsigned char* lds, const Params& p, bool need_ctx) {
;     ...
;     for (int item = BID; item < n_items; item += gridDim.x) {
;         int b, head, row0, nk;
;         if (item < 1024) {
;             const int rnd = item >> 8, w = item & 255, xcd = w & 7, slot = w >> 3, qb = slot & 7;
;             if (MLA) { const int grp = (rnd * 8 + xcd) * 4 + (slot >> 3); b = grp >> 4; head = grp & 15; }
;             else { const int grp = rnd * 8 + xcd; b = grp >> 2; head = (grp & 3) * 4 + (slot >> 3); }
;             row0 = b * 2048 + qb * 256; nk = NKEY;
;         }
;         else { const int it = item - 1024; b = it >> 4; head = it & 15; row0 = TL + b * 256; nk = 256; }
.Lamla_noresc_9:
	s_barrier
	s_add_i32 s59, s6, s31
	s_cmp_ge_i32 s59, s8
	s_cbranch_scc1 .Lamla_nonext
	s_cmpk_gt_i32 s59, 0x3ff
	s_cbranch_scc0 .Lamla_mainitem_next
	s_add_i32 s21, s59, 0xfffffc00
	s_lshr_b32 s15, s21, 4
	s_and_b32 s18, s21, 15
	s_lshl_b32 s20, s15, 8
	s_add_i32 s20, s20, 0x4000
	s_mov_b32 s7, 0
	s_branch .Lamla_decoded_next

.Lamla_nonext:
	ds_read_b64_tr_b16 v[192:193], v223 offset:3072
	ds_read_b64_tr_b16 v[194:195], v223 offset:4608
	ds_read_b64_tr_b16 v[196:197], v223 offset:3136
	ds_read_b64_tr_b16 v[198:199], v223 offset:4672
	s_waitcnt lgkmcnt(10)
	v_mfma_f32_32x32x16_bf16 v[0:15], v[176:179], v[96:99], v[0:15]
	v_max3_f32 v168, v64, v65, v66
	v_max3_f32 v170, v80, v81, v82
	v_max3_f32 v168, v168, v67, v68
	v_max3_f32 v170, v170, v83, v84
	v_max3_f32 v168, v168, v69, v70
	v_max3_f32 v170, v170, v85, v86
	v_max3_f32 v168, v168, v71, v72
	v_max3_f32 v170, v170, v87, v88
	v_max3_f32 v168, v168, v73, v74
	v_max3_f32 v170, v170, v89, v90
	v_max3_f32 v168, v168, v75, v76
	v_max3_f32 v170, v170, v91, v92
	s_mov_b32 s55, s52
	s_mov_b32 s52, s53
	s_mov_b32 s53, s54
	s_mov_b32 s54, s55
	s_mov_b32 s9, 0
	ds_read_b64_tr_b16 v[200:201], v223 offset:9216
	ds_read_b64_tr_b16 v[202:203], v223 offset:10752
	ds_read_b64_tr_b16 v[204:205], v223 offset:9280
	ds_read_b64_tr_b16 v[206:207], v223 offset:10816
	s_waitcnt lgkmcnt(12)
	v_mfma_f32_32x32x16_bf16 v[16:31], v[180:183], v[96:99], v[16:31]
	v_max3_f32 v168, v168, v77, v78
	v_max3_f32 v170, v170, v93, v94
	v_max_f32_e32 v168, v168, v79
	v_max_f32_e32 v170, v170, v95
	v_max_f32_e32 v168, v168, v170
	v_mov_b32_e32 v170, v168
	s_nop 1
	v_permlane32_swap_b32_e32 v168, v170
	v_max_f32_e32 v168, v168, v170
	v_mul_f32_e32 v168, 0x3e16c740, v168
	v_cmp_gt_f32_e32 vcc, v168, v164
	s_cbranch_vccz .Lamla_nors_10
	v_max_f32_e32 v170, v162, v168
	v_sub_f32_e32 v166, v162, v170
	v_exp_f32_e32 v166, v166
	v_mov_b32_e32 v162, v170
	v_add_f32_e32 v164, 0x41000000, v170
	v_xor_b32_e32 v163, 0x80000000, v170
	s_mov_b32 s9, 1
.Lamla_nors_10:
	v_add_u32_e32 v222, s53, v220
	v_mfma_f32_32x32x16_bf16 v[226:241], v[246:249], v[96:99], v[226:241]
	v_fmamk_f32 v64, v64, 0x3e16c740, v163
	v_fmamk_f32 v80, v80, 0x3e16c740, v163
	v_exp_f32_e32 v64, v64
	v_exp_f32_e32 v80, v80
	v_fmamk_f32 v65, v65, 0x3e16c740, v163
	v_fmamk_f32 v81, v81, 0x3e16c740, v163
	v_exp_f32_e32 v65, v65
	v_exp_f32_e32 v81, v81
	s_waitcnt lgkmcnt(10)
	v_mfma_f32_32x32x16_bf16 v[0:15], v[184:187], v[104:107], v[0:15]
	v_fmamk_f32 v66, v66, 0x3e16c740, v163
	v_fmamk_f32 v82, v82, 0x3e16c740, v163
	v_exp_f32_e32 v66, v66
	v_exp_f32_e32 v82, v82
	v_cvt_pk_bf16_f32 v96, v64, v65
	v_fmamk_f32 v67, v67, 0x3e16c740, v163
	v_fmamk_f32 v83, v83, 0x3e16c740, v163
	v_exp_f32_e32 v67, v67
	s_waitcnt lgkmcnt(8)
	v_mfma_f32_32x32x16_bf16 v[16:31], v[188:191], v[104:107], v[16:31]
	v_exp_f32_e32 v83, v83
	v_fmamk_f32 v68, v68, 0x3e16c740, v163
	v_fmamk_f32 v84, v84, 0x3e16c740, v163
	v_exp_f32_e32 v68, v68
	v_exp_f32_e32 v84, v84
	v_cvt_pk_bf16_f32 v97, v66, v67
	v_fmamk_f32 v69, v69, 0x3e16c740, v163
	v_fmamk_f32 v85, v85, 0x3e16c740, v163
	v_mfma_f32_32x32x16_bf16 v[226:241], v[246:249], v[104:107], v[226:241]
	v_cvt_pk_bf16_f32 v104, v80, v81
	v_cvt_pk_bf16_f32 v105, v82, v83
	v_exp_f32_e32 v69, v69
	v_exp_f32_e32 v85, v85
	v_fmamk_f32 v70, v70, 0x3e16c740, v163
	v_fmamk_f32 v86, v86, 0x3e16c740, v163
	v_exp_f32_e32 v70, v70
	v_exp_f32_e32 v86, v86
	v_cvt_pk_bf16_f32 v98, v68, v69
	s_waitcnt lgkmcnt(6)
	v_mfma_f32_32x32x16_bf16 v[0:15], v[192:195], v[100:103], v[0:15]
	v_cvt_pk_bf16_f32 v106, v84, v85
	v_fmamk_f32 v71, v71, 0x3e16c740, v163
	v_fmamk_f32 v87, v87, 0x3e16c740, v163
	v_exp_f32_e32 v71, v71
	v_exp_f32_e32 v87, v87
	v_fmamk_f32 v72, v72, 0x3e16c740, v163
	v_fmamk_f32 v88, v88, 0x3e16c740, v163
	v_exp_f32_e32 v72, v72
	ds_read_b64_tr_b16 v[176:177], v222 offset:0
	ds_read_b64_tr_b16 v[178:179], v222 offset:1536
	s_waitcnt lgkmcnt(6)
	v_mfma_f32_32x32x16_bf16 v[16:31], v[196:199], v[100:103], v[16:31]
	v_exp_f32_e32 v88, v88
	v_cvt_pk_bf16_f32 v99, v70, v71
	v_cvt_pk_bf16_f32 v107, v86, v87
	v_fmamk_f32 v73, v73, 0x3e16c740, v163
	v_fmamk_f32 v89, v89, 0x3e16c740, v163
	v_exp_f32_e32 v73, v73
	v_exp_f32_e32 v89, v89
	v_fmamk_f32 v74, v74, 0x3e16c740, v163
	ds_read_b64_tr_b16 v[180:181], v222 offset:64
	ds_read_b64_tr_b16 v[182:183], v222 offset:1600
	v_mfma_f32_32x32x16_bf16 v[226:241], v[246:249], v[100:103], v[226:241]
	v_fmamk_f32 v90, v90, 0x3e16c740, v163
	v_exp_f32_e32 v74, v74
	v_exp_f32_e32 v90, v90
	v_cvt_pk_bf16_f32 v100, v72, v73
	v_fmamk_f32 v75, v75, 0x3e16c740, v163
	v_fmamk_f32 v91, v91, 0x3e16c740, v163
	v_exp_f32_e32 v75, v75
	v_exp_f32_e32 v91, v91
	ds_read_b64_tr_b16 v[184:185], v222 offset:6144
	ds_read_b64_tr_b16 v[186:187], v222 offset:7680
	s_waitcnt lgkmcnt(8)
	v_mfma_f32_32x32x16_bf16 v[0:15], v[200:203], v[108:111], v[0:15]
	v_fmamk_f32 v76, v76, 0x3e16c740, v163
	v_fmamk_f32 v92, v92, 0x3e16c740, v163
	v_exp_f32_e32 v76, v76
	v_exp_f32_e32 v92, v92
	v_cvt_pk_bf16_f32 v101, v74, v75
	v_fmamk_f32 v77, v77, 0x3e16c740, v163
	v_fmamk_f32 v93, v93, 0x3e16c740, v163
	v_exp_f32_e32 v77, v77
	ds_read_b64_tr_b16 v[188:189], v222 offset:6208
	ds_read_b64_tr_b16 v[190:191], v222 offset:7744
	s_waitcnt lgkmcnt(8)
	v_mfma_f32_32x32x16_bf16 v[16:31], v[204:207], v[108:111], v[16:31]
	v_exp_f32_e32 v93, v93
	v_fmamk_f32 v78, v78, 0x3e16c740, v163
	v_fmamk_f32 v94, v94, 0x3e16c740, v163
	v_exp_f32_e32 v78, v78
	v_exp_f32_e32 v94, v94
	v_cvt_pk_bf16_f32 v102, v76, v77
	v_fmamk_f32 v79, v79, 0x3e16c740, v163
	v_fmamk_f32 v95, v95, 0x3e16c740, v163
	v_mfma_f32_32x32x16_bf16 v[226:241], v[246:249], v[108:111], v[226:241]
	v_cvt_pk_bf16_f32 v108, v88, v89
	v_cvt_pk_bf16_f32 v109, v90, v91
	v_cvt_pk_bf16_f32 v110, v92, v93
	v_exp_f32_e32 v79, v79
	v_exp_f32_e32 v95, v95
	v_cvt_pk_bf16_f32 v103, v78, v79
	v_cvt_pk_bf16_f32 v111, v94, v95
	s_cmp_lg_u32 s9, 0
	s_cbranch_scc0 .Lamla_noresc_11
	s_nop 15
	v_pk_mul_f32 v[0:1], v[0:1], v[166:167] op_sel_hi:[1,0]
	v_pk_mul_f32 v[2:3], v[2:3], v[166:167] op_sel_hi:[1,0]
	v_pk_mul_f32 v[4:5], v[4:5], v[166:167] op_sel_hi:[1,0]
	v_pk_mul_f32 v[6:7], v[6:7], v[166:167] op_sel_hi:[1,0]
	v_pk_mul_f32 v[8:9], v[8:9], v[166:167] op_sel_hi:[1,0]
	v_pk_mul_f32 v[10:11], v[10:11], v[166:167] op_sel_hi:[1,0]
	v_pk_mul_f32 v[12:13], v[12:13], v[166:167] op_sel_hi:[1,0]
	v_pk_mul_f32 v[14:15], v[14:15], v[166:167] op_sel_hi:[1,0]
	v_pk_mul_f32 v[16:17], v[16:17], v[166:167] op_sel_hi:[1,0]
	v_pk_mul_f32 v[18:19], v[18:19], v[166:167] op_sel_hi:[1,0]
	v_pk_mul_f32 v[20:21], v[20:21], v[166:167] op_sel_hi:[1,0]
	v_pk_mul_f32 v[22:23], v[22:23], v[166:167] op_sel_hi:[1,0]
	v_pk_mul_f32 v[24:25], v[24:25], v[166:167] op_sel_hi:[1,0]
	v_pk_mul_f32 v[26:27], v[26:27], v[166:167] op_sel_hi:[1,0]
	v_pk_mul_f32 v[28:29], v[28:29], v[166:167] op_sel_hi:[1,0]
	v_pk_mul_f32 v[30:31], v[30:31], v[166:167] op_sel_hi:[1,0]
	v_mul_f32_e32 v226, v226, v166
; #define AT_STEP(SC0, SC1, SN0, SN1, t, DOK, DOV) do { \
;             if (DOK) AT_GLOADK(((t) + 2) * 64); \
;             if (DOV) { AT_GLOADV(((t) + 1) * 64); AT_QK(SN0, SN1, ((t) + 1) & 1); } \
;             AT_SMPV(SC0, SC1, (t) & 1); \
;             if (DOK) AT_WRITEK((t) & 1); \
;             if (DOV) AT_WRITEV(((t) + 1) & 1); \
;             __syncthreads(); } while (0)
; #define AT_PK4(OX, jg) u32x2 { pk_bf16(OX[4 * (jg)] * inv, OX[4 * (jg) + 1] * inv), pk_bf16(OX[4 * (jg) + 2] * inv, OX[4 * (jg) + 3] * inv) }
; template <bool MLA>
; DI void attn_phase(const int TID, const int BID, LAS unsigned char* lds, const Params& p, bool need_ctx) {
;     ...
;         AT_STEP(sb0, sb1, sa0, sa1, t + 1, false, false);
;         __builtin_amdgcn_s_setprio(0);
;         lsum = xsum32(lsum);
;         const float inv = 1.f / lsum;
;         bf16_t* op = O + (size_t)(row0 + wid * 32 + r) * 1024 + head * 64 + 8 * hh;
;     ...
; #pragma unroll
;         for (int k = 0; k < 2; ++k) {
;             const u32x2 a = AT_PK4(o0, 2 * k), b2 = AT_PK4(o0, 2 * k + 1), c = AT_PK4(o1, 2 * k), d = AT_PK4(o1, 2 * k + 1);
;             const u32x2 s0 = __builtin_amdgcn_permlane32_swap(a[0], b2[0], false, false), s1 = __builtin_amdgcn_permlane32_swap(a[1], b2[1], false, false);
;             const u32x2 t0 = __builtin_amdgcn_permlane32_swap(c[0], d[0], false, false), t1 = __builtin_amdgcn_permlane32_swap(c[1], d[1], false, false);
;             const u32x4 w0 = {s0[0], s1[0], s0[1], s1[1]}, w1 = {t0[0], t1[0], t0[1], t1[1]};
;             *(u32x4*)(op + 16 * k) = w0; *(u32x4*)(op + 32 + 16 * k) = w1;
;         }
.Lamla_noresc_11:
	s_barrier
	ds_read_b64_tr_b16 v[192:193], v222 offset:3072
	ds_read_b64_tr_b16 v[194:195], v222 offset:4608
	ds_read_b64_tr_b16 v[196:197], v222 offset:3136
	ds_read_b64_tr_b16 v[198:199], v222 offset:4672
	s_waitcnt lgkmcnt(10)
	v_mfma_f32_32x32x16_bf16 v[0:15], v[176:179], v[96:99], v[0:15]
	s_mov_b32 s55, s52
	s_mov_b32 s52, s53
	s_mov_b32 s53, s54
	s_mov_b32 s54, s55
	ds_read_b64_tr_b16 v[200:201], v222 offset:9216
	ds_read_b64_tr_b16 v[202:203], v222 offset:10752
	ds_read_b64_tr_b16 v[204:205], v222 offset:9280
	ds_read_b64_tr_b16 v[206:207], v222 offset:10816
	s_waitcnt lgkmcnt(12)
	v_mfma_f32_32x32x16_bf16 v[16:31], v[180:183], v[96:99], v[16:31]
	v_mfma_f32_32x32x16_bf16 v[226:241], v[246:249], v[96:99], v[226:241]
	s_waitcnt lgkmcnt(10)
	v_mfma_f32_32x32x16_bf16 v[0:15], v[184:187], v[104:107], v[0:15]
	s_waitcnt lgkmcnt(8)
	v_mfma_f32_32x32x16_bf16 v[16:31], v[188:191], v[104:107], v[16:31]
	v_mfma_f32_32x32x16_bf16 v[226:241], v[246:249], v[104:107], v[226:241]
	s_waitcnt lgkmcnt(6)
	v_mfma_f32_32x32x16_bf16 v[0:15], v[192:195], v[100:103], v[0:15]
	s_waitcnt lgkmcnt(4)
	v_mfma_f32_32x32x16_bf16 v[16:31], v[196:199], v[100:103], v[16:31]
	v_mfma_f32_32x32x16_bf16 v[226:241], v[246:249], v[100:103], v[226:241]
	s_waitcnt lgkmcnt(2)
	v_mfma_f32_32x32x16_bf16 v[0:15], v[200:203], v[108:111], v[0:15]
	s_waitcnt lgkmcnt(0)
	v_mfma_f32_32x32x16_bf16 v[16:31], v[204:207], v[108:111], v[16:31]
	v_mfma_f32_32x32x16_bf16 v[226:241], v[246:249], v[108:111], v[226:241]
	s_setprio 0
	s_nop 11
	v_div_scale_f32 v148, s[60:61], v226, v226, 1.0
	v_rcp_f32_e32 v149, v148
	s_nop 0
	v_fma_f32 v150, -v148, v149, 1.0
	v_fmac_f32_e32 v149, v150, v149
	v_div_scale_f32 v150, vcc, 1.0, v226, 1.0
	v_mul_f32_e32 v151, v150, v149
	v_fma_f32 v173, -v148, v151, v150
	v_fmac_f32_e32 v151, v173, v149
	v_fma_f32 v148, -v148, v151, v150
	s_nop 1
	v_div_fmas_f32 v148, v148, v149, v151
	v_div_fixup_f32 v166, v148, v226, 1.0
	v_pk_mul_f32 v[0:1], v[0:1], v[166:167] op_sel_hi:[1,0]
	v_pk_mul_f32 v[2:3], v[2:3], v[166:167] op_sel_hi:[1,0]
	v_pk_mul_f32 v[4:5], v[4:5], v[166:167] op_sel_hi:[1,0]
	v_pk_mul_f32 v[6:7], v[6:7], v[166:167] op_sel_hi:[1,0]
	v_pk_mul_f32 v[8:9], v[8:9], v[166:167] op_sel_hi:[1,0]
	v_pk_mul_f32 v[10:11], v[10:11], v[166:167] op_sel_hi:[1,0]
	v_pk_mul_f32 v[12:13], v[12:13], v[166:167] op_sel_hi:[1,0]
	v_pk_mul_f32 v[14:15], v[14:15], v[166:167] op_sel_hi:[1,0]
	v_pk_mul_f32 v[16:17], v[16:17], v[166:167] op_sel_hi:[1,0]
	v_pk_mul_f32 v[18:19], v[18:19], v[166:167] op_sel_hi:[1,0]
	v_pk_mul_f32 v[20:21], v[20:21], v[166:167] op_sel_hi:[1,0]
	v_pk_mul_f32 v[22:23], v[22:23], v[166:167] op_sel_hi:[1,0]
	v_pk_mul_f32 v[24:25], v[24:25], v[166:167] op_sel_hi:[1,0]
	v_pk_mul_f32 v[26:27], v[26:27], v[166:167] op_sel_hi:[1,0]
	v_pk_mul_f32 v[28:29], v[28:29], v[166:167] op_sel_hi:[1,0]
	v_pk_mul_f32 v[30:31], v[30:31], v[166:167] op_sel_hi:[1,0]
	v_cvt_pk_bf16_f32 v96, v0, v1
	v_cvt_pk_bf16_f32 v97, v2, v3
	v_cvt_pk_bf16_f32 v98, v4, v5
	v_cvt_pk_bf16_f32 v99, v6, v7
	v_cvt_pk_bf16_f32 v100, v16, v17
	v_cvt_pk_bf16_f32 v101, v18, v19
	v_cvt_pk_bf16_f32 v102, v20, v21
	v_cvt_pk_bf16_f32 v103, v22, v23
	v_cvt_pk_bf16_f32 v104, v8, v9
	v_cvt_pk_bf16_f32 v105, v10, v11
	v_cvt_pk_bf16_f32 v106, v12, v13
	v_cvt_pk_bf16_f32 v107, v14, v15
	v_cvt_pk_bf16_f32 v108, v24, v25
	v_cvt_pk_bf16_f32 v109, v26, v27
	v_cvt_pk_bf16_f32 v110, v28, v29
	v_cvt_pk_bf16_f32 v111, v30, v31
	s_nop 1
	v_permlane32_swap_b32_e32 v96, v98
	v_permlane32_swap_b32_e32 v97, v99
	v_permlane32_swap_b32_e32 v100, v102
	v_permlane32_swap_b32_e32 v101, v103
	v_permlane32_swap_b32_e32 v104, v106
	v_permlane32_swap_b32_e32 v105, v107
	v_permlane32_swap_b32_e32 v108, v110
	v_permlane32_swap_b32_e32 v109, v111
	global_store_dwordx4 v172, v[96:99], s[16:17]
	global_store_dwordx4 v172, v[100:103], s[16:17] offset:64
	global_store_dwordx4 v172, v[104:107], s[16:17] offset:32
	global_store_dwordx4 v172, v[108:111], s[16:17] offset:96
	s_mov_b32 s6, s59
	s_mov_b64 s[16:17], s[62:63]
	s_cmp_ge_i32 s6, s8
	s_cbranch_scc0 .Lamla_item

.Lagqa_nors_1:
	v_fmamk_f32 v32, v32, 0x3e38aa3b, v163
	v_fmamk_f32 v48, v48, 0x3e38aa3b, v163
	v_exp_f32_e32 v32, v32
	v_exp_f32_e32 v48, v48
	v_fmamk_f32 v33, v33, 0x3e38aa3b, v163
	v_fmamk_f32 v49, v49, 0x3e38aa3b, v163
	v_exp_f32_e32 v33, v33
	v_exp_f32_e32 v49, v49
	ds_read_b128 v[140:143], v243 offset:13888
	global_load_dwordx4 v[208:211], v225, s[2:3]
	global_load_dwordx4 v[212:215], v225, s[4:5]
	s_add_u32 s2, s2, 0x2000
	s_addc_u32 s3, s3, 0
	s_add_u32 s4, s4, 0x2000
	s_addc_u32 s5, s5, 0
	v_add_u32_e32 v223, s53, v220
	v_add_u32_e32 v224, s54, v221
	s_waitcnt lgkmcnt(3)
	v_mfma_f32_32x32x16_bf16 v[64:79], v[144:147], v[116:119], v[64:79]
	v_fmamk_f32 v34, v34, 0x3e38aa3b, v163
	v_fmamk_f32 v50, v50, 0x3e38aa3b, v163
	v_exp_f32_e32 v34, v34
	v_exp_f32_e32 v50, v50
	v_cvt_pk_bf16_f32 v96, v32, v33
	v_cvt_pk_bf16_f32 v104, v48, v49
	v_fmamk_f32 v35, v35, 0x3e38aa3b, v163
	v_fmamk_f32 v51, v51, 0x3e38aa3b, v163
	v_exp_f32_e32 v35, v35
	v_exp_f32_e32 v51, v51
	v_fmamk_f32 v36, v36, 0x3e38aa3b, v163
	v_fmamk_f32 v52, v52, 0x3e38aa3b, v163
	ds_read_b128 v[144:147], v243 offset:9312
	ds_read_b64_tr_b16 v[176:177], v223 offset:0
	ds_read_b64_tr_b16 v[178:179], v223 offset:1536
	s_waitcnt lgkmcnt(5)
	v_mfma_f32_32x32x16_bf16 v[80:95], v[148:151], v[116:119], v[80:95]
	v_exp_f32_e32 v36, v36
	v_exp_f32_e32 v52, v52
	v_cvt_pk_bf16_f32 v97, v34, v35
	v_cvt_pk_bf16_f32 v105, v50, v51
	v_fmamk_f32 v37, v37, 0x3e38aa3b, v163
	v_fmamk_f32 v53, v53, 0x3e38aa3b, v163
	v_exp_f32_e32 v37, v37
	v_exp_f32_e32 v53, v53
	v_fmamk_f32 v38, v38, 0x3e38aa3b, v163
	v_fmamk_f32 v54, v54, 0x3e38aa3b, v163
	v_exp_f32_e32 v38, v38
	v_exp_f32_e32 v54, v54
	ds_read_b128 v[148:151], v243 offset:13920
	ds_read_b64_tr_b16 v[180:181], v223 offset:64
	ds_read_b64_tr_b16 v[182:183], v223 offset:1600
	s_waitcnt lgkmcnt(7)
	v_mfma_f32_32x32x16_bf16 v[64:79], v[136:139], v[120:123], v[64:79]
	v_cvt_pk_bf16_f32 v98, v36, v37
	v_cvt_pk_bf16_f32 v106, v52, v53
	v_fmamk_f32 v39, v39, 0x3e38aa3b, v163
	v_fmamk_f32 v55, v55, 0x3e38aa3b, v163
	v_exp_f32_e32 v39, v39
	v_exp_f32_e32 v55, v55
	v_fmamk_f32 v40, v40, 0x3e38aa3b, v163
	v_fmamk_f32 v56, v56, 0x3e38aa3b, v163
	v_exp_f32_e32 v40, v40
	v_exp_f32_e32 v56, v56
	v_cvt_pk_bf16_f32 v99, v38, v39
	v_cvt_pk_bf16_f32 v107, v54, v55
	ds_read_b64_tr_b16 v[184:185], v223 offset:6144
	ds_read_b64_tr_b16 v[186:187], v223 offset:7680
	s_waitcnt vmcnt(3)
	ds_write_b128 v218, v[152:155]
	s_waitcnt vmcnt(2)
	ds_write_b128 v224, v[156:159]
	s_waitcnt lgkmcnt(10)
	v_mfma_f32_32x32x16_bf16 v[80:95], v[140:143], v[120:123], v[80:95]
	v_fmamk_f32 v41, v41, 0x3e38aa3b, v163
	v_fmamk_f32 v57, v57, 0x3e38aa3b, v163
	v_exp_f32_e32 v41, v41
	v_exp_f32_e32 v57, v57
	v_fmamk_f32 v42, v42, 0x3e38aa3b, v163
	v_fmamk_f32 v58, v58, 0x3e38aa3b, v163
	v_exp_f32_e32 v42, v42
	v_exp_f32_e32 v58, v58
	v_cvt_pk_bf16_f32 v100, v40, v41
	v_cvt_pk_bf16_f32 v108, v56, v57
	v_fmamk_f32 v43, v43, 0x3e38aa3b, v163
	v_fmamk_f32 v59, v59, 0x3e38aa3b, v163
	v_exp_f32_e32 v43, v43
	ds_read_b64_tr_b16 v[188:189], v223 offset:6208
	ds_read_b64_tr_b16 v[190:191], v223 offset:7744
	s_waitcnt lgkmcnt(11)
	v_mfma_f32_32x32x16_bf16 v[64:79], v[144:147], v[124:127], v[64:79]
	v_exp_f32_e32 v59, v59
	v_fmamk_f32 v44, v44, 0x3e38aa3b, v163
	v_fmamk_f32 v60, v60, 0x3e38aa3b, v163
	v_exp_f32_e32 v44, v44
	v_exp_f32_e32 v60, v60
	v_cvt_pk_bf16_f32 v101, v42, v43
	v_cvt_pk_bf16_f32 v109, v58, v59
	v_fmamk_f32 v45, v45, 0x3e38aa3b, v163
	v_fmamk_f32 v61, v61, 0x3e38aa3b, v163
	v_exp_f32_e32 v45, v45
	v_exp_f32_e32 v61, v61
	s_waitcnt lgkmcnt(8)
	v_mfma_f32_32x32x16_bf16 v[80:95], v[148:151], v[124:127], v[80:95]
	v_fmamk_f32 v46, v46, 0x3e38aa3b, v163
	v_fmamk_f32 v62, v62, 0x3e38aa3b, v163
	v_exp_f32_e32 v46, v46
	v_exp_f32_e32 v62, v62
	v_cvt_pk_bf16_f32 v102, v44, v45
	v_cvt_pk_bf16_f32 v110, v60, v61
	v_fmamk_f32 v47, v47, 0x3e38aa3b, v163
	v_fmamk_f32 v63, v63, 0x3e38aa3b, v163
	v_exp_f32_e32 v47, v47
	v_exp_f32_e32 v63, v63
	v_cvt_pk_bf16_f32 v103, v46, v47
	v_cvt_pk_bf16_f32 v111, v62, v63
	s_waitcnt lgkmcnt(2)
	s_waitcnt lgkmcnt(0)
	s_barrier
	s_cmp_eq_u32 s7, 0
	s_cbranch_scc1 .Lagqa_tail
.Lagqa_loop:
	ds_read_b128 v[136:139], v243 offset:0
	ds_read_b128 v[140:143], v243 offset:4608
	ds_read_b128 v[144:147], v243 offset:32
	ds_read_b128 v[148:151], v243 offset:4640
	s_waitcnt lgkmcnt(10)
	v_mfma_f32_32x32x16_bf16 v[0:15], v[176:179], v[96:99], v[0:15]
	v_max3_f32 v168, v64, v65, v66
	v_max3_f32 v170, v80, v81, v82
	v_max3_f32 v168, v168, v67, v68
	v_max3_f32 v170, v170, v83, v84
	v_max3_f32 v168, v168, v69, v70
	v_max3_f32 v170, v170, v85, v86
	v_max3_f32 v168, v168, v71, v72
	s_mov_b32 s55, s52
	s_mov_b32 s52, s53
	s_mov_b32 s53, s54
	s_mov_b32 s54, s55
	s_mov_b32 s9, 0
	s_waitcnt lgkmcnt(8)
	v_mfma_f32_32x32x16_bf16 v[16:31], v[180:183], v[96:99], v[16:31]
	v_max3_f32 v170, v170, v87, v88
	v_max3_f32 v168, v168, v73, v74
	v_max3_f32 v170, v170, v89, v90
	v_max3_f32 v168, v168, v75, v76
	v_max3_f32 v170, v170, v91, v92
	v_max3_f32 v168, v168, v77, v78
	v_max3_f32 v170, v170, v93, v94
	global_load_dwordx4 v[152:155], v225, s[2:3]
	global_load_dwordx4 v[156:159], v225, s[4:5]
	s_add_u32 s2, s2, 0x2000
	s_addc_u32 s3, s3, 0
	s_add_u32 s4, s4, 0x2000
	s_addc_u32 s5, s5, 0
	v_add_u32_e32 v222, s53, v220
	v_add_u32_e32 v224, s54, v221
	v_mfma_f32_32x32x16_bf16 v[226:241], v[246:249], v[96:99], v[226:241]
	v_max_f32_e32 v168, v168, v79
	v_max_f32_e32 v170, v170, v95
	v_max_f32_e32 v168, v168, v170
	v_mov_b32_e32 v170, v168
	s_nop 1
	v_permlane32_swap_b32_e32 v168, v170
	v_max_f32_e32 v168, v168, v170
	v_mul_f32_e32 v168, 0x3e38aa3b, v168
	s_waitcnt lgkmcnt(3)
	v_mfma_f32_32x32x16_bf16 v[32:47], v[136:139], v[112:115], 0
	v_cmp_gt_f32_e32 vcc, v168, v164
	s_cbranch_vccz .Lagqa_nors_2
	v_max_f32_e32 v170, v162, v168
	v_sub_f32_e32 v166, v162, v170
	v_exp_f32_e32 v166, v166
	v_mov_b32_e32 v162, v170
	v_add_f32_e32 v164, 0x41000000, v170
	v_xor_b32_e32 v163, 0x80000000, v170
	s_mov_b32 s9, 1

.Lagqa_noresc_3:
	s_waitcnt lgkmcnt(8)
	s_barrier
	ds_read_b128 v[136:139], v243 offset:9216
	ds_read_b128 v[140:143], v243 offset:13824
	ds_read_b128 v[144:147], v243 offset:9248
	ds_read_b128 v[148:151], v243 offset:13856
	s_waitcnt lgkmcnt(10)
	v_mfma_f32_32x32x16_bf16 v[0:15], v[176:179], v[96:99], v[0:15]
	v_max3_f32 v168, v32, v33, v34
	v_max3_f32 v170, v48, v49, v50
	v_max3_f32 v168, v168, v35, v36
	v_max3_f32 v170, v170, v51, v52
	v_max3_f32 v168, v168, v37, v38
	v_max3_f32 v170, v170, v53, v54
	v_max3_f32 v168, v168, v39, v40
	s_mov_b32 s55, s52
	s_mov_b32 s52, s53
	s_mov_b32 s53, s54
	s_mov_b32 s54, s55
	s_mov_b32 s9, 0
	s_waitcnt lgkmcnt(8)
	v_mfma_f32_32x32x16_bf16 v[16:31], v[180:183], v[96:99], v[16:31]
	v_max3_f32 v170, v170, v55, v56
	v_max3_f32 v168, v168, v41, v42
	v_max3_f32 v170, v170, v57, v58
	v_max3_f32 v168, v168, v43, v44
	v_max3_f32 v170, v170, v59, v60
	v_max3_f32 v168, v168, v45, v46
	v_max3_f32 v170, v170, v61, v62
	global_load_dwordx4 v[208:211], v225, s[2:3]
	global_load_dwordx4 v[212:215], v225, s[4:5]
	s_add_u32 s2, s2, 0x2000
	s_addc_u32 s3, s3, 0
	s_add_u32 s4, s4, 0x2000
	s_addc_u32 s5, s5, 0
	v_add_u32_e32 v223, s53, v220
	v_add_u32_e32 v224, s54, v221
	v_mfma_f32_32x32x16_bf16 v[226:241], v[246:249], v[96:99], v[226:241]
	v_max_f32_e32 v168, v168, v47
	v_max_f32_e32 v170, v170, v63
	v_max_f32_e32 v168, v168, v170
	v_mov_b32_e32 v170, v168
	s_nop 1
	v_permlane32_swap_b32_e32 v168, v170
	v_max_f32_e32 v168, v168, v170
	v_mul_f32_e32 v168, 0x3e38aa3b, v168
	s_waitcnt lgkmcnt(3)
	v_mfma_f32_32x32x16_bf16 v[64:79], v[136:139], v[112:115], 0
	v_cmp_gt_f32_e32 vcc, v168, v164
	s_cbranch_vccz .Lagqa_nors_4
	v_max_f32_e32 v170, v162, v168
	v_sub_f32_e32 v166, v162, v170
	v_exp_f32_e32 v166, v166
	v_mov_b32_e32 v162, v170
	v_add_f32_e32 v164, 0x41000000, v170
	v_xor_b32_e32 v163, 0x80000000, v170
	s_mov_b32 s9, 1

; #define AT_STEP(SC0, SC1, SN0, SN1, t, DOK, DOV) do { \
;             if (DOK) AT_GLOADK(((t) + 2) * 64); \
;             if (DOV) { AT_GLOADV(((t) + 1) * 64); AT_QK(SN0, SN1, ((t) + 1) & 1); } \
;             AT_SMPV(SC0, SC1, (t) & 1); \
;             if (DOK) AT_WRITEK((t) & 1); \
;             if (DOV) AT_WRITEV(((t) + 1) & 1); \
;             __syncthreads(); } while (0)
; template <bool MLA>
; DI void attn_phase(const int TID, const int BID, LAS unsigned char* lds, const Params& p, bool need_ctx) {
;     ...
;         for (; t < ntile - 2; t += 2) {
;             AT_STEP(sa0, sa1, sb0, sb1, t, true, true);
;             AT_STEP(sb0, sb1, sa0, sa1, t + 1, true, true);
;         }
;         AT_STEP(sa0, sa1, sb0, sb1, t, false, true);
;         AT_STEP(sb0, sb1, sa0, sa1, t + 1, false, false);
.Lagqa_noresc_5:
	s_waitcnt lgkmcnt(8)
	s_barrier
	s_add_i32 s7, s7, -1
	s_cmp_lg_u32 s7, 0
	s_cbranch_scc1 .Lagqa_loop
.Lagqa_tail:
	ds_read_b128 v[136:139], v243 offset:0
	ds_read_b128 v[140:143], v243 offset:4608
	ds_read_b128 v[144:147], v243 offset:32
	ds_read_b128 v[148:151], v243 offset:4640
	s_waitcnt lgkmcnt(10)
	v_mfma_f32_32x32x16_bf16 v[0:15], v[176:179], v[96:99], v[0:15]
	v_max3_f32 v168, v64, v65, v66
	v_max3_f32 v170, v80, v81, v82
	v_max3_f32 v168, v168, v67, v68
	v_max3_f32 v170, v170, v83, v84
	v_max3_f32 v168, v168, v69, v70
	v_max3_f32 v170, v170, v85, v86
	v_max3_f32 v168, v168, v71, v72
	s_mov_b32 s55, s52
	s_mov_b32 s52, s53
	s_mov_b32 s53, s54
	s_mov_b32 s54, s55
	s_mov_b32 s9, 0
	s_waitcnt lgkmcnt(8)
	v_mfma_f32_32x32x16_bf16 v[16:31], v[180:183], v[96:99], v[16:31]
	v_max3_f32 v170, v170, v87, v88
	v_max3_f32 v168, v168, v73, v74
	v_max3_f32 v170, v170, v89, v90
	v_max3_f32 v168, v168, v75, v76
	v_max3_f32 v170, v170, v91, v92
	v_max3_f32 v168, v168, v77, v78
	v_max3_f32 v170, v170, v93, v94
	global_load_dwordx4 v[156:159], v225, s[4:5]
	s_add_u32 s4, s4, 0x2000
	s_addc_u32 s5, s5, 0
	v_add_u32_e32 v222, s53, v220
	v_add_u32_e32 v224, s54, v221
	v_mfma_f32_32x32x16_bf16 v[226:241], v[246:249], v[96:99], v[226:241]
	v_max_f32_e32 v168, v168, v79
	v_max_f32_e32 v170, v170, v95
	v_max_f32_e32 v168, v168, v170
	v_mov_b32_e32 v170, v168
	s_nop 1
	v_permlane32_swap_b32_e32 v168, v170
	v_max_f32_e32 v168, v168, v170
	v_mul_f32_e32 v168, 0x3e38aa3b, v168
	s_waitcnt lgkmcnt(3)
	v_mfma_f32_32x32x16_bf16 v[32:47], v[136:139], v[112:115], 0
	v_cmp_gt_f32_e32 vcc, v168, v164
	s_cbranch_vccz .Lagqa_nors_6
	v_max_f32_e32 v170, v162, v168
	v_sub_f32_e32 v166, v162, v170
	v_exp_f32_e32 v166, v166
	v_mov_b32_e32 v162, v170
	v_add_f32_e32 v164, 0x41000000, v170
	v_xor_b32_e32 v163, 0x80000000, v170
	s_mov_b32 s9, 1

.Lagqa_noresc_7:
	s_waitcnt lgkmcnt(8)
	s_barrier
	ds_read_b128 v[136:139], v243 offset:9216
	ds_read_b128 v[140:143], v243 offset:13824
	ds_read_b128 v[144:147], v243 offset:9248
	ds_read_b128 v[148:151], v243 offset:13856
	s_waitcnt lgkmcnt(10)
	v_mfma_f32_32x32x16_bf16 v[0:15], v[176:179], v[96:99], v[0:15]
	v_max3_f32 v168, v32, v33, v34
	v_max3_f32 v170, v48, v49, v50
	v_max3_f32 v168, v168, v35, v36
	v_max3_f32 v170, v170, v51, v52
	v_max3_f32 v168, v168, v37, v38
	v_max3_f32 v170, v170, v53, v54
	v_max3_f32 v168, v168, v39, v40
	s_mov_b32 s55, s52
	s_mov_b32 s52, s53
	s_mov_b32 s53, s54
	s_mov_b32 s54, s55
	s_mov_b32 s9, 0
	s_waitcnt lgkmcnt(8)
	v_mfma_f32_32x32x16_bf16 v[16:31], v[180:183], v[96:99], v[16:31]
	v_max3_f32 v170, v170, v55, v56
	v_max3_f32 v168, v168, v41, v42
	v_max3_f32 v170, v170, v57, v58
	v_max3_f32 v168, v168, v43, v44
	v_max3_f32 v170, v170, v59, v60
	v_max3_f32 v168, v168, v45, v46
	v_max3_f32 v170, v170, v61, v62
	v_add_u32_e32 v223, s53, v220
	v_add_u32_e32 v224, s54, v221
	v_mfma_f32_32x32x16_bf16 v[226:241], v[246:249], v[96:99], v[226:241]
	v_max_f32_e32 v168, v168, v47
	v_max_f32_e32 v170, v170, v63
	v_max_f32_e32 v168, v168, v170
	v_mov_b32_e32 v170, v168
	s_nop 1
	v_permlane32_swap_b32_e32 v168, v170
	v_max_f32_e32 v168, v168, v170
	v_mul_f32_e32 v168, 0x3e38aa3b, v168
	s_waitcnt lgkmcnt(3)
	v_mfma_f32_32x32x16_bf16 v[64:79], v[136:139], v[112:115], 0
	v_cmp_gt_f32_e32 vcc, v168, v164
	s_cbranch_vccz .Lagqa_nors_8
	v_max_f32_e32 v170, v162, v168
	v_sub_f32_e32 v166, v162, v170
	v_exp_f32_e32 v166, v166
	v_mov_b32_e32 v162, v170
	v_add_f32_e32 v164, 0x41000000, v170
	v_xor_b32_e32 v163, 0x80000000, v170
	s_mov_b32 s9, 1

; template <bool MLA>
; DI void attn_phase(const int TID, const int BID, LAS unsigned char* lds, const Params& p, bool need_ctx) {
;     ...
;     for (int item = BID; item < n_items; item += gridDim.x) {
;         int b, head, row0, nk;
;         if (item < 1024) {
;             const int rnd = item >> 8, w = item & 255, xcd = w & 7, slot = w >> 3, qb = slot & 7;
;             if (MLA) { const int grp = (rnd * 8 + xcd) * 4 + (slot >> 3); b = grp >> 4; head = grp & 15; }
;             else { const int grp = rnd * 8 + xcd; b = grp >> 2; head = (grp & 3) * 4 + (slot >> 3); }
;             row0 = b * 2048 + qb * 256; nk = NKEY;
;         }
;         else { const int it = item - 1024; b = it >> 4; head = it & 15; row0 = TL + b * 256; nk = 256; }
.Lagqa_noresc_9:
	s_waitcnt lgkmcnt(8)
	s_barrier
	s_add_i32 s59, s6, s31
	s_cmp_ge_i32 s59, s8
	s_cbranch_scc1 .Lagqa_nonext
	s_cmpk_gt_i32 s59, 0x3ff
	s_cbranch_scc0 .Lagqa_mainitem_next
	s_add_i32 s21, s59, 0xfffffc00
	s_lshr_b32 s15, s21, 4
	s_and_b32 s18, s21, 15
	s_lshl_b32 s20, s15, 8
	s_add_i32 s20, s20, 0x4000
	s_mov_b32 s7, 0
	s_branch .Lagqa_decoded_next

.Lagqa_nonext:
	ds_read_b64_tr_b16 v[192:193], v223 offset:3072
	ds_read_b64_tr_b16 v[194:195], v223 offset:4608
	ds_read_b64_tr_b16 v[196:197], v223 offset:3136
	ds_read_b64_tr_b16 v[198:199], v223 offset:4672
	s_waitcnt lgkmcnt(10)
	v_mfma_f32_32x32x16_bf16 v[0:15], v[176:179], v[96:99], v[0:15]
	v_max3_f32 v168, v64, v65, v66
	v_max3_f32 v170, v80, v81, v82
	v_max3_f32 v168, v168, v67, v68
	v_max3_f32 v170, v170, v83, v84
	v_max3_f32 v168, v168, v69, v70
	v_max3_f32 v170, v170, v85, v86
	v_max3_f32 v168, v168, v71, v72
	v_max3_f32 v170, v170, v87, v88
	v_max3_f32 v168, v168, v73, v74
	v_max3_f32 v170, v170, v89, v90
	v_max3_f32 v168, v168, v75, v76
	v_max3_f32 v170, v170, v91, v92
	s_mov_b32 s55, s52
	s_mov_b32 s52, s53
	s_mov_b32 s53, s54
	s_mov_b32 s54, s55
	s_mov_b32 s9, 0
	ds_read_b64_tr_b16 v[200:201], v223 offset:9216
	ds_read_b64_tr_b16 v[202:203], v223 offset:10752
	ds_read_b64_tr_b16 v[204:205], v223 offset:9280
	ds_read_b64_tr_b16 v[206:207], v223 offset:10816
	s_waitcnt lgkmcnt(12)
	v_mfma_f32_32x32x16_bf16 v[16:31], v[180:183], v[96:99], v[16:31]
	v_max3_f32 v168, v168, v77, v78
	v_max3_f32 v170, v170, v93, v94
	v_max_f32_e32 v168, v168, v79
	v_max_f32_e32 v170, v170, v95
	v_max_f32_e32 v168, v168, v170
	v_mov_b32_e32 v170, v168
	s_nop 1
	v_permlane32_swap_b32_e32 v168, v170
	v_max_f32_e32 v168, v168, v170
	v_mul_f32_e32 v168, 0x3e38aa3b, v168
	v_cmp_gt_f32_e32 vcc, v168, v164
	s_cbranch_vccz .Lagqa_nors_10
	v_max_f32_e32 v170, v162, v168
	v_sub_f32_e32 v166, v162, v170
	v_exp_f32_e32 v166, v166
	v_mov_b32_e32 v162, v170
	v_add_f32_e32 v164, 0x41000000, v170
	v_xor_b32_e32 v163, 0x80000000, v170
	s_mov_b32 s9, 1
.Lagqa_nors_10:
	v_add_u32_e32 v222, s53, v220
	v_mfma_f32_32x32x16_bf16 v[226:241], v[246:249], v[96:99], v[226:241]
	v_fmamk_f32 v64, v64, 0x3e38aa3b, v163
	v_fmamk_f32 v80, v80, 0x3e38aa3b, v163
	v_exp_f32_e32 v64, v64
	v_exp_f32_e32 v80, v80
	v_fmamk_f32 v65, v65, 0x3e38aa3b, v163
	v_fmamk_f32 v81, v81, 0x3e38aa3b, v163
	v_exp_f32_e32 v65, v65
	v_exp_f32_e32 v81, v81
	s_waitcnt lgkmcnt(10)
	v_mfma_f32_32x32x16_bf16 v[0:15], v[184:187], v[104:107], v[0:15]
	v_fmamk_f32 v66, v66, 0x3e38aa3b, v163
	v_fmamk_f32 v82, v82, 0x3e38aa3b, v163
	v_exp_f32_e32 v66, v66
	v_exp_f32_e32 v82, v82
	v_cvt_pk_bf16_f32 v96, v64, v65
	v_fmamk_f32 v67, v67, 0x3e38aa3b, v163
	v_fmamk_f32 v83, v83, 0x3e38aa3b, v163
	v_exp_f32_e32 v67, v67
	s_waitcnt lgkmcnt(8)
	v_mfma_f32_32x32x16_bf16 v[16:31], v[188:191], v[104:107], v[16:31]
	v_exp_f32_e32 v83, v83
	v_fmamk_f32 v68, v68, 0x3e38aa3b, v163
	v_fmamk_f32 v84, v84, 0x3e38aa3b, v163
	v_exp_f32_e32 v68, v68
	v_exp_f32_e32 v84, v84
	v_cvt_pk_bf16_f32 v97, v66, v67
	v_fmamk_f32 v69, v69, 0x3e38aa3b, v163
	v_fmamk_f32 v85, v85, 0x3e38aa3b, v163
	v_mfma_f32_32x32x16_bf16 v[226:241], v[246:249], v[104:107], v[226:241]
	v_cvt_pk_bf16_f32 v104, v80, v81
	v_cvt_pk_bf16_f32 v105, v82, v83
	v_exp_f32_e32 v69, v69
	v_exp_f32_e32 v85, v85
	v_fmamk_f32 v70, v70, 0x3e38aa3b, v163
	v_fmamk_f32 v86, v86, 0x3e38aa3b, v163
	v_exp_f32_e32 v70, v70
	v_exp_f32_e32 v86, v86
	v_cvt_pk_bf16_f32 v98, v68, v69
	s_waitcnt lgkmcnt(6)
	v_mfma_f32_32x32x16_bf16 v[0:15], v[192:195], v[100:103], v[0:15]
	v_cvt_pk_bf16_f32 v106, v84, v85
	v_fmamk_f32 v71, v71, 0x3e38aa3b, v163
	v_fmamk_f32 v87, v87, 0x3e38aa3b, v163
	v_exp_f32_e32 v71, v71
	v_exp_f32_e32 v87, v87
	v_fmamk_f32 v72, v72, 0x3e38aa3b, v163
	v_fmamk_f32 v88, v88, 0x3e38aa3b, v163
	v_exp_f32_e32 v72, v72
	ds_read_b64_tr_b16 v[176:177], v222 offset:0
	ds_read_b64_tr_b16 v[178:179], v222 offset:1536
	s_waitcnt lgkmcnt(6)
	v_mfma_f32_32x32x16_bf16 v[16:31], v[196:199], v[100:103], v[16:31]
	v_exp_f32_e32 v88, v88
	v_cvt_pk_bf16_f32 v99, v70, v71
	v_cvt_pk_bf16_f32 v107, v86, v87
	v_fmamk_f32 v73, v73, 0x3e38aa3b, v163
	v_fmamk_f32 v89, v89, 0x3e38aa3b, v163
	v_exp_f32_e32 v73, v73
	v_exp_f32_e32 v89, v89
	v_fmamk_f32 v74, v74, 0x3e38aa3b, v163
	ds_read_b64_tr_b16 v[180:181], v222 offset:64
	ds_read_b64_tr_b16 v[182:183], v222 offset:1600
	v_mfma_f32_32x32x16_bf16 v[226:241], v[246:249], v[100:103], v[226:241]
	v_fmamk_f32 v90, v90, 0x3e38aa3b, v163
	v_exp_f32_e32 v74, v74
	v_exp_f32_e32 v90, v90
	v_cvt_pk_bf16_f32 v100, v72, v73
	v_fmamk_f32 v75, v75, 0x3e38aa3b, v163
	v_fmamk_f32 v91, v91, 0x3e38aa3b, v163
	v_exp_f32_e32 v75, v75
	v_exp_f32_e32 v91, v91
	ds_read_b64_tr_b16 v[184:185], v222 offset:6144
	ds_read_b64_tr_b16 v[186:187], v222 offset:7680
	s_waitcnt lgkmcnt(8)
	v_mfma_f32_32x32x16_bf16 v[0:15], v[200:203], v[108:111], v[0:15]
	v_fmamk_f32 v76, v76, 0x3e38aa3b, v163
	v_fmamk_f32 v92, v92, 0x3e38aa3b, v163
	v_exp_f32_e32 v76, v76
	v_exp_f32_e32 v92, v92
	v_cvt_pk_bf16_f32 v101, v74, v75
	v_fmamk_f32 v77, v77, 0x3e38aa3b, v163
	v_fmamk_f32 v93, v93, 0x3e38aa3b, v163
	v_exp_f32_e32 v77, v77
	ds_read_b64_tr_b16 v[188:189], v222 offset:6208
	ds_read_b64_tr_b16 v[190:191], v222 offset:7744
	s_waitcnt lgkmcnt(8)
	v_mfma_f32_32x32x16_bf16 v[16:31], v[204:207], v[108:111], v[16:31]
	v_exp_f32_e32 v93, v93
	v_fmamk_f32 v78, v78, 0x3e38aa3b, v163
	v_fmamk_f32 v94, v94, 0x3e38aa3b, v163
	v_exp_f32_e32 v78, v78
	v_exp_f32_e32 v94, v94
	v_cvt_pk_bf16_f32 v102, v76, v77
	v_fmamk_f32 v79, v79, 0x3e38aa3b, v163
	v_fmamk_f32 v95, v95, 0x3e38aa3b, v163
	v_mfma_f32_32x32x16_bf16 v[226:241], v[246:249], v[108:111], v[226:241]
	v_cvt_pk_bf16_f32 v108, v88, v89
	v_cvt_pk_bf16_f32 v109, v90, v91
	v_cvt_pk_bf16_f32 v110, v92, v93
	v_exp_f32_e32 v79, v79
	v_exp_f32_e32 v95, v95
	v_cvt_pk_bf16_f32 v103, v78, v79
	v_cvt_pk_bf16_f32 v111, v94, v95
	s_cmp_lg_u32 s9, 0
	s_cbranch_scc0 .Lagqa_noresc_11
	s_nop 15
	v_pk_mul_f32 v[0:1], v[0:1], v[166:167] op_sel_hi:[1,0]
	v_pk_mul_f32 v[2:3], v[2:3], v[166:167] op_sel_hi:[1,0]
	v_pk_mul_f32 v[4:5], v[4:5], v[166:167] op_sel_hi:[1,0]
	v_pk_mul_f32 v[6:7], v[6:7], v[166:167] op_sel_hi:[1,0]
	v_pk_mul_f32 v[8:9], v[8:9], v[166:167] op_sel_hi:[1,0]
	v_pk_mul_f32 v[10:11], v[10:11], v[166:167] op_sel_hi:[1,0]
	v_pk_mul_f32 v[12:13], v[12:13], v[166:167] op_sel_hi:[1,0]
	v_pk_mul_f32 v[14:15], v[14:15], v[166:167] op_sel_hi:[1,0]
	v_pk_mul_f32 v[16:17], v[16:17], v[166:167] op_sel_hi:[1,0]
	v_pk_mul_f32 v[18:19], v[18:19], v[166:167] op_sel_hi:[1,0]
	v_pk_mul_f32 v[20:21], v[20:21], v[166:167] op_sel_hi:[1,0]
	v_pk_mul_f32 v[22:23], v[22:23], v[166:167] op_sel_hi:[1,0]
	v_pk_mul_f32 v[24:25], v[24:25], v[166:167] op_sel_hi:[1,0]
	v_pk_mul_f32 v[26:27], v[26:27], v[166:167] op_sel_hi:[1,0]
	v_pk_mul_f32 v[28:29], v[28:29], v[166:167] op_sel_hi:[1,0]
	v_pk_mul_f32 v[30:31], v[30:31], v[166:167] op_sel_hi:[1,0]
	v_mul_f32_e32 v226, v226, v166
